# grid-barrier poll loops sleep 4 instead of 1 between polls (less polling traffic while stragglers finish); otherwise the previous best
# baseline (speedup 1.0000x reference)
.LBB0_288:
	s_and_b32 s14, s18, 0xff
	s_mov_b64 s[12:13], -1
	s_cmp_lg_u32 s14, 0
	s_mov_b64 s[16:17], -1
	s_sleep 4
	s_cbranch_scc0 .LBB0_291
	s_and_b64 vcc, exec, s[16:17]
	s_cbranch_vccz .LBB0_287

.LBB0_367:
	s_and_b32 s16, s18, 0xff
	s_mov_b64 s[14:15], -1
	s_cmp_lg_u32 s16, 0
	s_mov_b64 s[20:21], -1
	s_sleep 4
	s_cbranch_scc0 .LBB0_370
	s_and_b64 vcc, exec, s[20:21]
	s_cbranch_vccz .LBB0_366
